# attention key loop: 9 v_pk_add_f32 split into scalar v_add_f32 pairs (packed f32 is slow beside MFMAs), bit-identical
# baseline (speedup 1.0000x reference)
; #define MFMA(a, b, c) __builtin_amdgcn_mfma_f32_32x32x16_bf16((a), (b), (c), 0, 0, 0)
; DI void attn_item64(const Params& p, int it, char* smem) {
;     ...
;   for (int kt = 0; kt < NKT; ++kt) {
;     const char* cur = smem + (kt & 1) * STAGE;
;     const bool more = kt + 1 < NKT;
;     if (more) {
;       const bf16_t* kn = Kb + (size_t)(kt + 1) * 64 * QKD; const bf16_t* vn = Vb + (kt + 1) * 64;
;       char* nx = smem + ((kt + 1) & 1) * STAGE;
;       GLDS(kn + kgo0, nx + klo0); if (k1v) GLDS(kn + kgo1, nx + klo1);
;       rv0 = *(const uint4*)(vn + vgo0);
;     }
;     SB_;
; #pragma unroll
;     for (int t2 = 0; t2 < 2; ++t2) {
;       const char* kpe = cur + (t2 * 32 + r) * KROW + swo;
;       const char* kpo = kpe - 2 * sb32;
;       f32x16 sa, sb;
;       { const bf16x8 kf = *(const bf16x8*)(kpe); sa = MFMA(kf, qfa[0], sinit); sb = MFMA(kf, qfb[0], sinit); }
; #pragma unroll
;       for (int c = 1; c < 6; ++c) { const bf16x8 kf = *(const bf16x8*)(((c & 1) ? kpo : kpe) + c * 32); sa = MFMA(kf, qfa[c], sa); sb = MFMA(kf, qfb[c], sb); }
;       SB_;
;       float lsa = 0.f, lsb = 0.f;
; #pragma unroll
;       for (int i = 0; i < 16; ++i) { const float e = __builtin_amdgcn_exp2f(sa[i]); sa[i] = e; lsa += e; const float f = __builtin_amdgcn_exp2f(sb[i]); sb[i] = f; lsb += f; }
;       la += lsa; lb += lsb;
;       SB_;
; #pragma unroll
;       for (int s2 = 0; s2 < 2; ++s2) {
;         uint4 pu, pv;
;         pu.x = pk_bf16(sa[8 * s2 + 0], sa[8 * s2 + 1]); pu.y = pk_bf16(sa[8 * s2 + 2], sa[8 * s2 + 3]); pu.z = pk_bf16(sa[8 * s2 + 4], sa[8 * s2 + 5]); pu.w = pk_bf16(sa[8 * s2 + 6], sa[8 * s2 + 7]);
;         pv.x = pk_bf16(sb[8 * s2 + 0], sb[8 * s2 + 1]); pv.y = pk_bf16(sb[8 * s2 + 2], sb[8 * s2 + 3]); pv.z = pk_bf16(sb[8 * s2 + 4], sb[8 * s2 + 5]); pv.w = pk_bf16(sb[8 * s2 + 6], sb[8 * s2 + 7]);
;         const bf16x8 pa_ = __builtin_bit_cast(bf16x8, pu), pb_ = __builtin_bit_cast(bf16x8, pv);
; #pragma unroll
;         for (int vt = 0; vt < 2; ++vt) {
;           const char* vp = cur + KBYTES + (vt * 32 + r) * VROW + (t2 * 32 + 16 * s2 + 4 * hh) * 2;
;           const uint2 lo = *(const uint2*)(vp), hi = *(const uint2*)(vp + 16);
;           uint4 vu; vu.x = lo.x; vu.y = lo.y; vu.z = hi.x; vu.w = hi.y;
;           const bf16x8 vf = __builtin_bit_cast(bf16x8, vu);
;           oa[vt] = MFMA(vf, pa_, oa[vt]);
;           ob[vt] = MFMA(vf, pb_, ob[vt]);
.LBB0_548:
	s_or_b64 exec, exec, s[4:5]
	global_load_dwordx4 v[160:163], v[170:171], off
	s_cmp_eq_u32 s7, 1
	s_cselect_b32 s4, 0, 0x5200
	v_or_b32_e32 v80, s4, v211
	v_add_u32_e32 v80, v80, v210
	v_or_b32_e32 v81, s4, v164
	v_add_u32_e32 v168, v80, v212
	v_add3_u32 v213, v80, v207, v206
	v_add_u32_e32 v80, s6, v209
	v_add_u32_e32 v188, v168, v206
	v_add_u32_e32 v195, v81, v208
	v_add_u32_e32 v238, 0x3000, v80
	ds_read_b128 v[176:179], v168
	ds_read_b128 v[242:245], v188 offset:32
	ds_read_b128 v[180:183], v168 offset:64
	ds_read_b128 v[246:249], v188 offset:96
	ds_read_b128 v[184:187], v168 offset:128
	s_waitcnt lgkmcnt(4)
	v_mfma_f32_32x32x16_bf16 v[80:95], v[176:179], v[152:155], v[64:79]
	v_mfma_f32_32x32x16_bf16 v[96:111], v[176:179], v[156:159], v[64:79]
	ds_read_b128 v[176:179], v188 offset:160
	s_waitcnt lgkmcnt(4)
	v_mfma_f32_32x32x16_bf16 v[80:95], v[242:245], v[136:139], v[80:95]
	v_mfma_f32_32x32x16_bf16 v[96:111], v[242:245], v[140:143], v[96:111]
	s_waitcnt lgkmcnt(3)
	v_mfma_f32_32x32x16_bf16 v[80:95], v[180:183], v[144:147], v[80:95]
	v_mfma_f32_32x32x16_bf16 v[96:111], v[180:183], v[148:151], v[96:111]
	s_waitcnt lgkmcnt(2)
	v_mfma_f32_32x32x16_bf16 v[80:95], v[246:249], v[112:115], v[80:95]
	v_mfma_f32_32x32x16_bf16 v[96:111], v[246:249], v[124:127], v[96:111]
	s_waitcnt lgkmcnt(1)
	v_mfma_f32_32x32x16_bf16 v[80:95], v[184:187], v[128:131], v[80:95]
	v_mfma_f32_32x32x16_bf16 v[96:111], v[184:187], v[132:135], v[96:111]
	s_waitcnt lgkmcnt(0)
	v_mfma_f32_32x32x16_bf16 v[80:95], v[176:179], v[116:119], v[80:95]
	v_mfma_f32_32x32x16_bf16 v[96:111], v[176:179], v[120:123], v[96:111]
	v_add_u32_e32 v239, 0x3000, v195
	v_add_u32_e32 v240, 0x4000, v195
	ds_read2_b64 v[242:245], v239 offset1:2
	ds_read2_b64 v[246:249], v240 offset0:32 offset1:34
	s_nop 10
	v_exp_f32_e32 v214, v80
	v_exp_f32_e32 v215, v81
	v_exp_f32_e32 v216, v82
	v_exp_f32_e32 v217, v83
	v_add_f32_e32 v80, 0, v214
	v_exp_f32_e32 v218, v84
	v_add_f32_e32 v80, v215, v80
	v_exp_f32_e32 v219, v85
	v_add_f32_e32 v80, v216, v80
	v_exp_f32_e32 v222, v86
	v_add_f32_e32 v80, v217, v80
	v_add_f32_e32 v80, v218, v80
	v_add_f32_e32 v80, v219, v80
	v_exp_f32_e32 v96, v96
	v_exp_f32_e32 v97, v97
	v_exp_f32_e32 v98, v98
	v_exp_f32_e32 v99, v99
	v_exp_f32_e32 v100, v100
	v_exp_f32_e32 v101, v101
	v_exp_f32_e32 v102, v102
	v_exp_f32_e32 v188, v87
	v_exp_f32_e32 v189, v103
	v_exp_f32_e32 v186, v88
	v_exp_f32_e32 v187, v104
	v_exp_f32_e32 v190, v89
	v_exp_f32_e32 v191, v105
	v_exp_f32_e32 v192, v90
	v_exp_f32_e32 v193, v106
	v_exp_f32_e32 v180, v91
	v_exp_f32_e32 v181, v107
	v_exp_f32_e32 v182, v92
	v_exp_f32_e32 v183, v108
	v_exp_f32_e32 v184, v93
	v_exp_f32_e32 v185, v109
	v_exp_f32_e32 v176, v94
	v_exp_f32_e32 v177, v110
	v_exp_f32_e32 v178, v95
	v_exp_f32_e32 v179, v111
	v_add_f32_e32 v194, v222, v80
	v_cvt_pk_bf16_f32 v84, v214, v215
	v_cvt_pk_bf16_f32 v85, v216, v217
	v_cvt_pk_bf16_f32 v86, v218, v219
	v_cvt_pk_bf16_f32 v87, v222, v188
	v_cvt_pk_bf16_f32 v88, v96, v97
	v_cvt_pk_bf16_f32 v89, v98, v99
	v_cvt_pk_bf16_f32 v90, v100, v101
	v_cvt_pk_bf16_f32 v91, v102, v189
	s_waitcnt lgkmcnt(0)
	v_mfma_f32_32x32x16_bf16 v[48:63], v[242:245], v[84:87], v[48:63]
	v_mfma_f32_32x32x16_bf16 v[32:47], v[242:245], v[88:91], v[32:47]
	ds_read2_b64 v[214:217], v239 offset0:4 offset1:6
	ds_read2_b64 v[222:225], v240 offset0:36 offset1:38
	s_waitcnt lgkmcnt(2)
	v_mfma_f32_32x32x16_bf16 v[16:31], v[246:249], v[84:87], v[16:31]
	v_add_f32_e32 v84, 0, v96
	v_add_f32_e32 v84, v97, v84
	v_add_f32_e32 v84, v98, v84
	v_add_f32_e32 v84, v99, v84
	v_add_f32_e32 v84, v100, v84
	v_add_f32_e32 v84, v101, v84
	v_add_f32_e32 v195, v102, v84
	v_mfma_f32_32x32x16_bf16 v[0:15], v[246:249], v[88:91], v[0:15]
	ds_read_b128 v[226:229], v168 offset:6144
	ds_read_b128 v[242:245], v213 offset:32
	ds_read_b128 v[230:233], v168 offset:6208
	ds_read_b128 v[246:249], v213 offset:96
	ds_read_b128 v[234:237], v168 offset:6272
	s_waitcnt lgkmcnt(4)
	v_mfma_f32_32x32x16_bf16 v[80:95], v[226:229], v[152:155], v[64:79]
	v_mfma_f32_32x32x16_bf16 v[96:111], v[226:229], v[156:159], v[64:79]
	ds_read_b128 v[226:229], v213 offset:160
	s_waitcnt lgkmcnt(4)
	v_mfma_f32_32x32x16_bf16 v[80:95], v[242:245], v[136:139], v[80:95]
	v_mfma_f32_32x32x16_bf16 v[96:111], v[242:245], v[140:143], v[96:111]
	s_waitcnt lgkmcnt(3)
	v_mfma_f32_32x32x16_bf16 v[80:95], v[230:233], v[144:147], v[80:95]
	v_mfma_f32_32x32x16_bf16 v[96:111], v[230:233], v[148:151], v[96:111]
	s_waitcnt lgkmcnt(2)
	v_mfma_f32_32x32x16_bf16 v[80:95], v[246:249], v[112:115], v[80:95]
	v_mfma_f32_32x32x16_bf16 v[96:111], v[246:249], v[124:127], v[96:111]
	s_waitcnt lgkmcnt(1)
	v_mfma_f32_32x32x16_bf16 v[80:95], v[234:237], v[128:131], v[80:95]
	v_mfma_f32_32x32x16_bf16 v[96:111], v[234:237], v[132:135], v[96:111]
	s_waitcnt lgkmcnt(0)
; #define MFMA(a, b, c) __builtin_amdgcn_mfma_f32_32x32x16_bf16((a), (b), (c), 0, 0, 0)
; DI unsigned pk_bf16(float lo, float hi) { f32x2v v = {lo, hi}; bf16x2v b = __builtin_convertvector(v, bf16x2v); return __builtin_bit_cast(unsigned, b); }
; #define SB_ __builtin_amdgcn_sched_barrier(0)
; DI void attn_item64(const Params& p, int it, char* smem) {
;     ...
;       float lsa = 0.f, lsb = 0.f;
; #pragma unroll
;       for (int i = 0; i < 16; ++i) { const float e = __builtin_amdgcn_exp2f(sa[i]); sa[i] = e; lsa += e; const float f = __builtin_amdgcn_exp2f(sb[i]); sb[i] = f; lsb += f; }
;       la += lsa; lb += lsb;
;     ...
; #pragma unroll
;       for (int s2 = 0; s2 < 2; ++s2) {
;         uint4 pu, pv;
;         pu.x = pk_bf16(sa[8 * s2 + 0], sa[8 * s2 + 1]); pu.y = pk_bf16(sa[8 * s2 + 2], sa[8 * s2 + 3]); pu.z = pk_bf16(sa[8 * s2 + 4], sa[8 * s2 + 5]); pu.w = pk_bf16(sa[8 * s2 + 6], sa[8 * s2 + 7]);
;         pv.x = pk_bf16(sb[8 * s2 + 0], sb[8 * s2 + 1]); pv.y = pk_bf16(sb[8 * s2 + 2], sb[8 * s2 + 3]); pv.z = pk_bf16(sb[8 * s2 + 4], sb[8 * s2 + 5]); pv.w = pk_bf16(sb[8 * s2 + 6], sb[8 * s2 + 7]);
;         const bf16x8 pa_ = __builtin_bit_cast(bf16x8, pu), pb_ = __builtin_bit_cast(bf16x8, pv);
; #pragma unroll
;         for (int vt = 0; vt < 2; ++vt) {
;           const char* vp = cur + KBYTES + (vt * 32 + r) * VROW + (t2 * 32 + 16 * s2 + 4 * hh) * 2;
;           const uint2 lo = *(const uint2*)(vp), hi = *(const uint2*)(vp + 16);
;           uint4 vu; vu.x = lo.x; vu.y = lo.y; vu.z = hi.x; vu.w = hi.y;
;           const bf16x8 vf = __builtin_bit_cast(bf16x8, vu);
;           oa[vt] = MFMA(vf, pa_, oa[vt]);
;           ob[vt] = MFMA(vf, pb_, ob[vt]);
;         }
;       }
;       SB_;
;     }
	v_mfma_f32_32x32x16_bf16 v[80:95], v[226:229], v[116:119], v[80:95]
	v_mfma_f32_32x32x16_bf16 v[96:111], v[226:229], v[120:123], v[96:111]
	s_waitcnt vmcnt(0)
	ds_write2_b64 v238, v[160:161], v[162:163] offset1:1
	v_cvt_pk_bf16_f32 v242, v186, v190
	v_cvt_pk_bf16_f32 v243, v192, v180
	v_cvt_pk_bf16_f32 v244, v182, v184
	v_cvt_pk_bf16_f32 v245, v176, v178
	v_cvt_pk_bf16_f32 v246, v187, v191
	v_cvt_pk_bf16_f32 v247, v193, v181
	v_cvt_pk_bf16_f32 v248, v183, v185
	v_cvt_pk_bf16_f32 v249, v177, v179
	s_nop 3
	v_exp_f32_e32 v168, v80
	v_exp_f32_e32 v213, v81
	v_exp_f32_e32 v233, v96
	v_exp_f32_e32 v96, v82
	v_exp_f32_e32 v234, v97
	v_exp_f32_e32 v97, v83
	v_add_f32_e32 v80, 0, v168
	v_exp_f32_e32 v235, v98
	v_exp_f32_e32 v98, v84
	v_mfma_f32_32x32x16_bf16 v[48:63], v[214:217], v[242:245], v[48:63]
	v_add_f32_e32 v80, v213, v80
	v_exp_f32_e32 v236, v99
	v_exp_f32_e32 v99, v85
	v_add_f32_e32 v80, v96, v80
	v_add_f32_e32 v80, v97, v80
	v_add_f32_e32 v80, v98, v80
	v_exp_f32_e32 v237, v100
	v_exp_f32_e32 v241, v101
	v_exp_f32_e32 v100, v86
	v_exp_f32_e32 v101, v102
	v_exp_f32_e32 v102, v87
	v_exp_f32_e32 v103, v103
	v_mfma_f32_32x32x16_bf16 v[16:31], v[222:225], v[242:245], v[16:31]
	v_exp_f32_e32 v218, v88
	v_exp_f32_e32 v219, v104
	v_exp_f32_e32 v104, v89
	v_exp_f32_e32 v105, v105
	v_exp_f32_e32 v226, v90
	v_exp_f32_e32 v227, v106
	v_exp_f32_e32 v106, v91
	v_exp_f32_e32 v107, v107
	v_mfma_f32_32x32x16_bf16 v[32:47], v[214:217], v[246:249], v[32:47]
	v_exp_f32_e32 v228, v92
	v_exp_f32_e32 v229, v108
	v_exp_f32_e32 v108, v93
	v_exp_f32_e32 v109, v109
	v_exp_f32_e32 v230, v94
	v_exp_f32_e32 v231, v110
	v_exp_f32_e32 v110, v95
	v_exp_f32_e32 v111, v111
	v_mfma_f32_32x32x16_bf16 v[0:15], v[222:225], v[246:249], v[0:15]
	v_add_f32_e32 v232, v99, v80
	v_cvt_pk_bf16_f32 v88, v233, v234
	v_cvt_pk_bf16_f32 v89, v235, v236
	v_cvt_pk_bf16_f32 v90, v237, v241
	v_cvt_pk_bf16_f32 v91, v101, v103
	ds_read2_b64 v[80:83], v239 offset0:8 offset1:10
	ds_read2_b64 v[246:249], v240 offset0:40 offset1:42
	v_cvt_pk_bf16_f32 v84, v168, v213
	v_cvt_pk_bf16_f32 v85, v96, v97
	v_cvt_pk_bf16_f32 v86, v98, v99
	v_cvt_pk_bf16_f32 v87, v100, v102
	s_waitcnt lgkmcnt(0)
	s_nop 0
	v_mfma_f32_32x32x16_bf16 v[48:63], v[80:83], v[84:87], v[48:63]
	v_mfma_f32_32x32x16_bf16 v[32:47], v[80:83], v[88:91], v[32:47]
	ds_read2_b64 v[92:95], v239 offset0:12 offset1:14
	ds_read2_b64 v[96:99], v240 offset0:44 offset1:46
	s_waitcnt lgkmcnt(2)
	v_mfma_f32_32x32x16_bf16 v[16:31], v[246:249], v[84:87], v[16:31]
	v_add_f32_e32 v84, 0, v233
	v_add_f32_e32 v84, v234, v84
	v_add_f32_e32 v84, v235, v84
	v_add_f32_e32 v84, v236, v84
	v_add_f32_e32 v84, v237, v84
	v_add_f32_e32 v233, v241, v84
	v_add_f32_e32 v84, v188, v194
	v_add_f32_e32 v85, v189, v195
	v_mfma_f32_32x32x16_bf16 v[0:15], v[246:249], v[88:91], v[0:15]
	v_add_f32_e64 v80, v186, v84
	v_add_f32_e64 v81, v187, v85
	v_add_f32_e64 v90, v100, v232
	v_add_f32_e64 v91, v101, v233
	v_add_f32_e64 v80, v190, v80
	v_add_f32_e64 v81, v191, v81
	v_add_f32_e32 v90, v102, v90
	v_add_f32_e32 v91, v103, v91
	v_add_f32_e32 v84, v192, v80
	v_add_f32_e32 v85, v193, v81
	v_cvt_pk_bf16_f32 v80, v218, v104
	v_add_f32_e32 v84, v180, v84
	v_add_f32_e32 v85, v181, v85
	v_cvt_pk_bf16_f32 v81, v226, v106
	v_add_f32_e32 v84, v182, v84
	v_add_f32_e32 v85, v183, v85
	v_cvt_pk_bf16_f32 v82, v228, v108
	v_cvt_pk_bf16_f32 v83, v230, v110
	v_add_f32_e32 v88, v184, v84
	v_add_f32_e32 v89, v185, v85
	v_cvt_pk_bf16_f32 v84, v219, v105
	v_cvt_pk_bf16_f32 v85, v227, v107
	v_cvt_pk_bf16_f32 v86, v229, v109
	v_cvt_pk_bf16_f32 v87, v231, v111
	v_add_f32_e32 v90, v218, v90
	v_add_f32_e32 v91, v219, v91
	s_waitcnt lgkmcnt(1)
	v_mfma_f32_32x32x16_bf16 v[48:63], v[92:95], v[80:83], v[48:63]
	v_add_f32_e64 v90, v104, v90
	v_add_f32_e64 v91, v105, v91
	v_add_f32_e64 v88, v176, v88
	v_add_f32_e64 v89, v177, v89
	v_add_f32_e64 v88, v178, v88
	v_add_f32_e64 v89, v179, v89
	v_add_f32_e32 v88, v166, v88
	v_add_f32_e32 v89, v167, v89
	v_mfma_f32_32x32x16_bf16 v[32:47], v[92:95], v[84:87], v[32:47]
	s_waitcnt lgkmcnt(0)
	v_mfma_f32_32x32x16_bf16 v[16:31], v[96:99], v[80:83], v[16:31]
	v_add_f32_e64 v80, v226, v90
	v_add_f32_e64 v81, v227, v91
	v_add_f32_e64 v80, v106, v80
	v_add_f32_e64 v81, v107, v81
	v_add_f32_e64 v80, v228, v80
	v_add_f32_e64 v81, v229, v81
	v_add_f32_e32 v80, v108, v80
	v_add_f32_e32 v81, v109, v81
	v_mfma_f32_32x32x16_bf16 v[0:15], v[96:99], v[84:87], v[0:15]
	v_add_f32_e64 v80, v230, v80
	v_add_f32_e64 v81, v231, v81
	v_add_f32_e64 v80, v110, v80
	v_add_f32_e64 v81, v111, v81
	v_add_f32_e64 v166, v88, v80
	v_add_f32_e64 v167, v89, v81
	s_add_i32 s8, s8, 1
	v_lshl_add_u64 v[170:171], v[170:171], 0, s[30:31]
	v_lshl_add_u64 v[172:173], v[172:173], 0, s[34:35]
	s_cmp_lg_u32 s8, 36
	v_lshl_add_u64 v[174:175], v[174:175], 0, s[34:35]
	s_waitcnt lgkmcnt(0)
	s_barrier
	s_cbranch_scc0 .LBB0_551
